# v31 + GLA prep gate dots as packed f32: (wf,wb) weight pairs loaded into an aligned bank, (a[k],a[16+k]) via ds_read2_b32, one v_pk_fma_f32 per term (same fma chain order)
# baseline (speedup 1.0000x reference)
; LPHASE void phase_gla_prep(char* ws_, const float* x_, float* out_, const float* meta_, int nseq_, char* lds) {
;     ...
;     { bf16_t* dst = (bf16_t*)(gp + GP_VT) + ((size_t)ch * 4 + hd) * 256 * 64;
; #pragma unroll
;       for (int q = 0; q < 4; ++q) { const int i8 = (tid & 7) * 8, c = (tid >> 3) + 64 * q; bf16x8 w;
; #pragma unroll
;         for (int e = 0; e < 8; ++e) w[e] = (short)vt[(i8 + e) * 264 + c];
;         *(bf16x8*)(dst + c * 64 + i8) = w; } }
;     { float wf[16], wb[16];
; #pragma unroll
;       for (int k = 0; k < 16; ++k) { wf[k] = smg[S_WAF + k * 512 + hd * 128 + d]; wb[k] = smg[S_WAB + k * 512 + hd * 128 + d]; }
.LBB0_505:
	s_or_b64 exec, exec, s[28:29]
	s_ashr_i32 s1, s0, 31
	s_lshl_b64 s[38:39], s[0:1], 2
	s_or_b32 s38, s38, s30
	v_lshlrev_b32_e32 v0, 3, v16
	s_lshl_b64 s[2:3], s[38:39], 15
	s_add_u32 s0, s52, s2
	v_and_b32_e32 v0, 56, v0
	s_addc_u32 s1, s53, s3
	v_ashrrev_i32_e32 v1, 3, v16
	v_lshlrev_b32_e32 v132, 1, v0
	v_lshl_add_u64 v[8:9], s[0:1], 0, v[132:133]
	v_mul_u32_u24_e32 v4, 0x210, v0
	v_lshlrev_b32_e32 v5, 1, v1
	v_readlane_b32 s0, v254, 31
	s_waitcnt lgkmcnt(0)
	s_barrier
	v_add3_u32 v4, s0, v5, v4
	ds_read_u16 v5, v4 offset:3168
	ds_read_u16 v6, v4 offset:3696
	ds_read_u16 v12, v4 offset:3296
	ds_read_u16 v13, v4 offset:3824
	ds_read_u16 v14, v4 offset:3424
	ds_read_u16 v15, v4 offset:3952
	ds_read_u16 v17, v4 offset:4080
	ds_read_u16 v22, v4 offset:3552
	s_waitcnt lgkmcnt(6)
	v_perm_b32 v7, v6, v5, s84
	ds_read_u16 v5, v4 offset:2112
	ds_read_u16 v6, v4 offset:2640
	ds_read_u16 v18, v4 offset:2240
	ds_read_u16 v19, v4 offset:2768
	ds_read_u16 v23, v4 offset:2368
	ds_read_u16 v24, v4 offset:2896
	ds_read_u16 v25, v4 offset:3024
	ds_read_u16 v60, v4 offset:2496
	s_waitcnt lgkmcnt(6)
	v_perm_b32 v6, v6, v5, s84
	ds_read_u16 v5, v4 offset:1056
	ds_read_u16 v10, v4 offset:1584
	ds_read_u16 v61, v4 offset:1184
	ds_read_u16 v62, v4 offset:1712
	ds_read_u16 v63, v4 offset:1312
	ds_read_u16 v64, v4 offset:1840
	ds_read_u16 v65, v4 offset:1968
	ds_read_u16 v66, v4 offset:1440
	v_lshlrev_b32_e32 v20, 6, v1
	s_waitcnt lgkmcnt(6)
	v_perm_b32 v5, v10, v5, s84
	ds_read_u16 v10, v4
	ds_read_u16 v11, v4 offset:528
	ds_read_u16 v67, v4 offset:128
	ds_read_u16 v68, v4 offset:656
	ds_read_u16 v69, v4 offset:256
	ds_read_u16 v70, v4 offset:784
	ds_read_u16 v71, v4 offset:912
	ds_read_u16 v72, v4 offset:384
	v_ashrrev_i32_e32 v21, 31, v20
	s_waitcnt lgkmcnt(6)
	v_perm_b32 v4, v11, v10, s84
	v_lshl_add_u64 v[10:11], v[20:21], 1, v[8:9]
	global_store_dwordx4 v[10:11], v[4:7], off
	s_add_i32 s0, s12, 0x980
	v_mov_b32_e32 v84, 0
	v_perm_b32 v6, v19, v18, s84
	v_add_u32_e32 v18, 0x1000, v20
	v_ashrrev_i32_e32 v19, 31, v18
	v_perm_b32 v7, v13, v12, s84
	v_perm_b32 v5, v62, v61, s84
	s_waitcnt lgkmcnt(4)
	v_perm_b32 v4, v68, v67, s84
	v_lshl_add_u64 v[10:11], v[18:19], 1, v[8:9]
	global_store_dwordx4 v[10:11], v[4:7], off
	v_add_u32_e32 v10, 0x2000, v20
	v_ashrrev_i32_e32 v11, 31, v10
	v_perm_b32 v7, v15, v14, s84
	v_perm_b32 v6, v24, v23, s84
	v_perm_b32 v5, v64, v63, s84
	s_waitcnt lgkmcnt(2)
	v_perm_b32 v4, v70, v69, s84
	v_lshl_add_u64 v[10:11], v[10:11], 1, v[8:9]
	global_store_dwordx4 v[10:11], v[4:7], off
	v_add_u32_e32 v10, 0x3000, v20
	v_ashrrev_i32_e32 v11, 31, v10
	v_perm_b32 v7, v17, v22, s84
	v_perm_b32 v6, v25, v60, s84
	v_perm_b32 v5, v65, v66, s84
	s_waitcnt lgkmcnt(0)
	v_perm_b32 v4, v71, v72, s84
	v_lshl_add_u64 v[8:9], v[10:11], 1, v[8:9]
	global_store_dwordx4 v[8:9], v[4:7], off
	v_mov_b32_e32 v25, v133
	s_nop 0
	v_or_b32_e32 v4, s0, v2
	v_lshlrev_b32_e32 v132, 2, v4
	v_lshl_add_u64 v[22:23], s[34:35], 0, v[132:133]
	s_add_i32 s0, s12, 0x2b80
	v_add_co_u32_e32 v70, vcc, s4, v22
	v_or_b32_e32 v5, s0, v2
	s_nop 0
	v_addc_co_u32_e32 v71, vcc, 0, v23, vcc
	v_lshlrev_b32_e32 v24, 2, v5
	v_add_co_u32_e32 v6, vcc, s72, v22
	v_lshl_add_u64 v[60:61], s[34:35], 0, v[24:25]
	s_nop 0
	v_addc_co_u32_e32 v7, vcc, 0, v23, vcc
	v_add_co_u32_e32 v72, vcc, s4, v60
	s_add_i32 s0, s12, 0x2980
	s_nop 0
	v_addc_co_u32_e32 v73, vcc, 0, v61, vcc
	v_add_co_u32_e32 v4, vcc, s72, v60
	s_addk_i32 s12, 0x4b80
	s_nop 0
	v_addc_co_u32_e32 v5, vcc, 0, v61, vcc
	v_add_co_u32_e32 v14, vcc, s92, v22
	v_or_b32_e32 v25, s12, v2
	s_nop 0
	v_addc_co_u32_e32 v15, vcc, 0, v23, vcc
	v_add_co_u32_e32 v74, vcc, s73, v22
	global_load_dword v172, v[6:7], off offset:-4096
	global_load_dword v173, v[4:5], off offset:-4096
	global_load_dword v176, v[6:7], off
	global_load_dword v177, v[4:5], off
	global_load_dword v179, v[4:5], off offset:2048
	global_load_dword v180, v[14:15], off offset:-4096
	s_nop 0
	global_load_dword v184, v[14:15], off
	global_load_dword v178, v[6:7], off offset:2048
	v_addc_co_u32_e32 v75, vcc, 0, v23, vcc
	v_add_co_u32_e32 v76, vcc, s73, v60
	v_or_b32_e32 v17, s0, v2
	s_nop 0
	v_addc_co_u32_e32 v77, vcc, 0, v61, vcc
	v_add_co_u32_e32 v8, vcc, s92, v60
	v_lshlrev_b32_e32 v17, 2, v17
	s_nop 0
	v_addc_co_u32_e32 v9, vcc, 0, v61, vcc
	v_add_co_u32_e32 v78, vcc, s69, v22
	s_movk_i32 s0, 0x2040
	s_nop 0
	v_addc_co_u32_e32 v79, vcc, 0, v23, vcc
	v_add_co_u32_e32 v80, vcc, s69, v60
	s_mov_b32 s12, 0
	s_nop 0
	v_addc_co_u32_e32 v81, vcc, 0, v61, vcc
	global_load_dword v181, v[8:9], off offset:-4096
	global_load_dword v185, v[8:9], off
	global_load_dword v187, v[8:9], off offset:2048
	s_nop 0
	global_load_dword v188, v[78:79], off offset:-4096
	global_load_dword v189, v[80:81], off offset:-4096
	global_load_dword v192, v[78:79], off
	global_load_dword v194, v[78:79], off offset:2048
	global_load_dword v186, v[14:15], off offset:2048
	v_add_co_u32_e32 v78, vcc, s74, v22
	global_load_dword v193, v[80:81], off
	global_load_dword v195, v[80:81], off offset:2048
	v_addc_co_u32_e32 v79, vcc, 0, v23, vcc
	v_add_co_u32_e32 v82, vcc, s74, v60
	s_nop 1
	v_addc_co_u32_e32 v83, vcc, 0, v61, vcc
	v_add_co_u32_e32 v80, vcc, s75, v22
	s_nop 1
	v_addc_co_u32_e32 v81, vcc, 0, v23, vcc
	v_add_co_u32_e32 v60, vcc, s75, v60
	global_load_dword v174, v[70:71], off offset:2048
	s_nop 0
	global_load_dword v175, v[72:73], off offset:2048
	s_nop 0
	global_load_dword v182, v[74:75], off offset:2048
	global_load_dword v183, v[76:77], off offset:2048
	global_load_dword v190, v[78:79], off offset:2048
	global_load_dword v191, v[82:83], off offset:2048
	global_load_dword v196, v[80:81], off
	global_load_dword v198, v[80:81], off offset:2048
	v_lshlrev_b32_e32 v79, 2, v25
	v_addc_co_u32_e32 v61, vcc, 0, v61, vcc
	global_load_dword v168, v132, s[34:35]
	global_load_dword v169, v24, s[34:35]
	global_load_dword v171, v24, s[34:35] offset:2048
	global_load_dword v170, v132, s[34:35] offset:2048
	s_nop 0
	global_load_dword v197, v[60:61], off
	global_load_dword v199, v[60:61], off offset:2048
	global_load_dword v78, v17, s[34:35]
	s_nop 0
	global_load_dword v79, v79, s[34:35]
	v_lshlrev_b32_e32 v17, 4, v49
	v_lshlrev_b32_e32 v60, 11, v49
	v_mul_lo_u32 v81, v49, s0
	v_lshlrev_b32_e32 v61, 2, v2
	v_add_u32_e32 v80, 0, v60
	v_add3_u32 v81, v81, v61, 0
	v_mov_b32_e32 v83, 0
	v_mov_b32_e32 v82, v17
; LPHASE void phase_gla_prep(char* ws_, const float* x_, float* out_, const float* meta_, int nseq_, char* lds) {
;     ...
; #pragma unroll 2
;       for (int ii = 0; ii < 16; ++ii) { const int i = ig * 16 + ii; float sf = bfv, sb = bbv; const float* a = af + i * 32;
; #pragma unroll
;         for (int k = 0; k < 16; ++k) { sf += a[k] * wf[k]; sb += a[16 + k] * wb[k]; }
;         float lf = (fminf(sf, 0.f) - __logf(1.f + __expf(-fabsf(sf)))) * (1.f / 16.f), lb = (fminf(sb, 0.f) - __logf(1.f + __expf(-fabsf(sb)))) * (1.f / 16.f);
;         if (ismeta && i >= 16) { lf = 0.f; lb = 0.f; }
;         lgF[i * LGP + d] = lf; lgB[i * LGP + d] = lb; tfl += lf; tbl += lb; }
.LBB0_506:
	v_add_u32_e32 v85, s12, v80
	v_add_u32_e32 v96, 0x10200, v85
	ds_read2_b32 v[100:101], v96 offset0:0 offset1:16
	ds_read2_b32 v[102:103], v96 offset0:1 offset1:17
	ds_read2_b32 v[104:105], v96 offset0:2 offset1:18
	ds_read2_b32 v[106:107], v96 offset0:3 offset1:19
	ds_read2_b32 v[108:109], v96 offset0:4 offset1:20
	ds_read2_b32 v[110:111], v96 offset0:5 offset1:21
	ds_read2_b32 v[112:113], v96 offset0:6 offset1:22
	ds_read2_b32 v[114:115], v96 offset0:7 offset1:23
	ds_read2_b32 v[116:117], v96 offset0:8 offset1:24
	ds_read2_b32 v[118:119], v96 offset0:9 offset1:25
	ds_read2_b32 v[120:121], v96 offset0:10 offset1:26
	ds_read2_b32 v[122:123], v96 offset0:11 offset1:27
	ds_read2_b32 v[124:125], v96 offset0:12 offset1:28
	ds_read2_b32 v[126:127], v96 offset0:13 offset1:29
	ds_read2_b32 v[128:129], v96 offset0:14 offset1:30
	ds_read2_b32 v[130:131], v96 offset0:15 offset1:31
	ds_read2_b32 v[136:137], v96 offset0:32 offset1:48
	ds_read2_b32 v[138:139], v96 offset0:33 offset1:49
	ds_read2_b32 v[140:141], v96 offset0:34 offset1:50
	ds_read2_b32 v[142:143], v96 offset0:35 offset1:51
	ds_read2_b32 v[144:145], v96 offset0:36 offset1:52
	ds_read2_b32 v[146:147], v96 offset0:37 offset1:53
	ds_read2_b32 v[148:149], v96 offset0:38 offset1:54
	ds_read2_b32 v[150:151], v96 offset0:39 offset1:55
	ds_read2_b32 v[152:153], v96 offset0:40 offset1:56
	ds_read2_b32 v[154:155], v96 offset0:41 offset1:57
	ds_read2_b32 v[156:157], v96 offset0:42 offset1:58
	ds_read2_b32 v[158:159], v96 offset0:43 offset1:59
	ds_read2_b32 v[160:161], v96 offset0:44 offset1:60
	ds_read2_b32 v[162:163], v96 offset0:45 offset1:61
	ds_read2_b32 v[164:165], v96 offset0:46 offset1:62
	ds_read2_b32 v[166:167], v96 offset0:47 offset1:63
	s_waitcnt vmcnt(0) lgkmcnt(0)
	s_addk_i32 s12, 0x100
	v_pk_fma_f32 v[94:95], v[168:169], v[100:101], v[78:79]
	v_pk_fma_f32 v[94:95], v[170:171], v[102:103], v[94:95]
	v_pk_fma_f32 v[94:95], v[172:173], v[104:105], v[94:95]
	v_pk_fma_f32 v[94:95], v[174:175], v[106:107], v[94:95]
	v_pk_fma_f32 v[94:95], v[176:177], v[108:109], v[94:95]
	v_pk_fma_f32 v[94:95], v[178:179], v[110:111], v[94:95]
	v_pk_fma_f32 v[94:95], v[180:181], v[112:113], v[94:95]
	v_pk_fma_f32 v[94:95], v[182:183], v[114:115], v[94:95]
	v_pk_fma_f32 v[94:95], v[184:185], v[116:117], v[94:95]
	v_pk_fma_f32 v[94:95], v[186:187], v[118:119], v[94:95]
	v_pk_fma_f32 v[94:95], v[188:189], v[120:121], v[94:95]
	v_pk_fma_f32 v[94:95], v[190:191], v[122:123], v[94:95]
	v_pk_fma_f32 v[94:95], v[192:193], v[124:125], v[94:95]
	v_pk_fma_f32 v[94:95], v[194:195], v[126:127], v[94:95]
	v_pk_fma_f32 v[94:95], v[196:197], v[128:129], v[94:95]
	v_pk_fma_f32 v[94:95], v[198:199], v[130:131], v[94:95]
	v_min_f32_e32 v87, 0, v94
	v_mul_f32_e64 v88, |v94|, s6
	v_exp_f32_e32 v88, v88
	s_nop 0
	v_add_f32_e32 v88, 1.0, v88
	v_log_f32_e32 v88, v88
	s_nop 0
	v_mul_f32_e32 v89, 0x3f317217, v88
	v_fma_f32 v89, v88, s13, -v89
	v_fmac_f32_e32 v89, 0x3377d1cf, v88
	v_fmac_f32_e32 v89, 0x3f317217, v88
	v_mov_b32_e32 v88, v89
	v_sub_f32_e32 v87, v87, v88
	v_min_f32_e32 v88, 0, v95
	v_mul_f32_e64 v86, |v95|, s6
	v_exp_f32_e32 v86, v86
	v_mul_f32_e32 v87, 0x3d800000, v87
	v_add_f32_e32 v86, 1.0, v86
	v_log_f32_e32 v86, v86
	s_nop 0
	v_mul_f32_e32 v89, 0x3f317217, v86
	v_fma_f32 v89, v86, s13, -v89
	v_fmac_f32_e32 v89, 0x3377d1cf, v86
	v_fmac_f32_e32 v89, 0x3f317217, v86
	v_mov_b32_e32 v86, v89
	v_sub_f32_e32 v86, v88, v86
	v_cmp_lt_i32_e32 vcc, 15, v82
	v_mul_f32_e32 v86, 0x3d800000, v86
	s_and_b64 s[0:1], s[26:27], vcc
	v_cndmask_b32_e64 v86, v86, 0, s[0:1]
	v_cndmask_b32_e64 v87, v87, 0, s[0:1]
	ds_write_b32 v81, v87
	ds_write_b32 v81, v86 offset:33024
	v_add_f32_e32 v84, v84, v86
	v_add_f32_e32 v83, v83, v87
	v_pk_fma_f32 v[94:95], v[168:169], v[136:137], v[78:79]
	v_pk_fma_f32 v[94:95], v[170:171], v[138:139], v[94:95]
	v_pk_fma_f32 v[94:95], v[172:173], v[140:141], v[94:95]
	v_pk_fma_f32 v[94:95], v[174:175], v[142:143], v[94:95]
	v_pk_fma_f32 v[94:95], v[176:177], v[144:145], v[94:95]
	v_pk_fma_f32 v[94:95], v[178:179], v[146:147], v[94:95]
	v_pk_fma_f32 v[94:95], v[180:181], v[148:149], v[94:95]
	v_pk_fma_f32 v[94:95], v[182:183], v[150:151], v[94:95]
	v_pk_fma_f32 v[94:95], v[184:185], v[152:153], v[94:95]
	v_pk_fma_f32 v[94:95], v[186:187], v[154:155], v[94:95]
	v_pk_fma_f32 v[94:95], v[188:189], v[156:157], v[94:95]
	v_pk_fma_f32 v[94:95], v[190:191], v[158:159], v[94:95]
	v_pk_fma_f32 v[94:95], v[192:193], v[160:161], v[94:95]
	v_pk_fma_f32 v[94:95], v[194:195], v[162:163], v[94:95]
	v_pk_fma_f32 v[94:95], v[196:197], v[164:165], v[94:95]
	v_pk_fma_f32 v[94:95], v[198:199], v[166:167], v[94:95]
	v_mul_f32_e64 v87, |v94|, s6
	v_exp_f32_e32 v87, v87
	v_min_f32_e32 v86, 0, v94
	v_add_f32_e32 v87, 1.0, v87
	v_log_f32_e32 v87, v87
	s_nop 0
	v_mul_f32_e32 v88, 0x3f317217, v87
	v_fma_f32 v88, v87, s13, -v88
	v_fmac_f32_e32 v88, 0x3377d1cf, v87
	v_fmac_f32_e32 v88, 0x3f317217, v87
	v_mov_b32_e32 v87, v88
	v_sub_f32_e32 v86, v86, v87
	v_min_f32_e32 v87, 0, v95
	v_mul_f32_e64 v85, |v95|, s6
	v_exp_f32_e32 v85, v85
	v_mul_f32_e32 v86, 0x3d800000, v86
	v_add_f32_e32 v85, 1.0, v85
	v_log_f32_e32 v85, v85
	s_nop 0
	v_mul_f32_e32 v88, 0x3f317217, v85
	v_fma_f32 v88, v85, s13, -v88
	v_fmac_f32_e32 v88, 0x3377d1cf, v85
	v_fmac_f32_e32 v88, 0x3f317217, v85
	v_mov_b32_e32 v85, v88
	v_sub_f32_e32 v85, v87, v85
	v_cmp_lt_i32_e32 vcc, 14, v82
	v_mul_f32_e32 v85, 0x3d800000, v85
	s_and_b64 s[0:1], s[26:27], vcc
	v_cndmask_b32_e64 v85, v85, 0, s[0:1]
	v_cndmask_b32_e64 v86, v86, 0, s[0:1]
	ds_write_b32 v81, v86 offset:516
	ds_write_b32 v81, v85 offset:33540
	v_add_f32_e32 v83, v83, v86
	v_add_f32_e32 v84, v84, v85
	v_add_u32_e32 v82, 2, v82
	v_add_u32_e32 v81, 0x408, v81
	s_cmpk_eq_i32 s12, 0x800
	s_cbranch_scc0 .LBB0_506
	v_and_b32_e32 v4, 0x3fffff80, v16
	v_lshl_add_u32 v6, v2, 2, s85
	v_lshl_add_u32 v5, v16, 2, s85
	v_lshl_add_u32 v4, v4, 2, v6
	ds_write_b32 v5, v83
	ds_write_b32 v4, v84 offset:2048
	s_waitcnt lgkmcnt(0)
	s_barrier
	ds_read2st64_b32 v[10:11], v6 offset1:2
	ds_read2st64_b32 v[8:9], v6 offset0:4 offset1:6
	ds_read2st64_b32 v[4:5], v6 offset0:8 offset1:10
	ds_read2st64_b32 v[6:7], v6 offset0:12 offset1:14
	s_movk_i32 s0, 0x80
	v_cmp_gt_u32_e32 vcc, s0, v16
	s_movk_i32 s0, 0x7f
	s_waitcnt lgkmcnt(3)
	v_add_f32_e32 v11, v10, v11
	v_cmp_lt_u32_e64 s[0:1], s0, v16
	v_mov_b32_e32 v13, 0
	s_and_saveexec_b64 s[26:27], s[0:1]
	s_cbranch_execz .LBB0_513
	v_cmp_lt_i32_e64 s[0:1], 1, v49
	s_mov_b64 s[28:29], 0
	s_and_saveexec_b64 s[30:31], s[0:1]
	s_xor_b64 s[42:43], exec, s[30:31]
	s_cbranch_execnz .LBB0_527
	s_or_saveexec_b64 s[42:43], s[42:43]
	v_mov_b32_e32 v13, v11
	s_xor_b64 exec, exec, s[42:43]
	s_cbranch_execnz .LBB0_530
